# attention: K/V/bias staging double-buffered in LDS (address registers toggle by 0x12000 per unit), the per-unit top-of-loop workgroup barrier removed
# speedup vs baseline: 1.0056x; 1.0024x over previous
.LBB0_313:
	s_mov_b32 s100, 0x12000
	s_and_b64 vcc, exec, s[8:9]
	s_cbranch_vccnz .LBB0_438
	v_and_b32_e32 v3, 64, v209
	v_xor_b32_e32 v2, 1, v209
	v_add_u32_e32 v3, 64, v3
	v_cmp_lt_i32_e32 vcc, v2, v3
	v_lshlrev_b32_e32 v0, 2, v73
	v_readlane_b32 s58, v253, 8
	v_cndmask_b32_e32 v2, v209, v2, vcc
	v_lshlrev_b32_e32 v174, 2, v2
	v_xor_b32_e32 v2, 2, v209
	v_cmp_lt_i32_e32 vcc, v2, v3
	v_readlane_b32 s12, v253, 23
	v_add_u32_e32 v173, s58, v0
	v_cndmask_b32_e32 v2, v209, v2, vcc
	v_lshlrev_b32_e32 v175, 2, v2
	v_xor_b32_e32 v2, 4, v209
	v_and_b32_e32 v0, 0x1fc, v0
	s_and_b64 s[8:9], s[92:93], exec
	v_readlane_b32 s13, v253, 24
	v_cmp_lt_i32_e32 vcc, v2, v3
	v_add_u32_e32 v69, 0, v0
	v_xor_b32_e32 v0, 16, v209
	s_cselect_b32 s0, 5, 3
	s_and_b64 s[8:9], s[12:13], exec
	v_cndmask_b32_e32 v2, v209, v2, vcc
	v_cmp_lt_i32_e32 vcc, v0, v3
	s_cselect_b32 s47, 7, s0
	s_add_i32 s56, s56, -1
	s_lshl_b32 s24, s28, 4
	v_cndmask_b32_e32 v0, v209, v0, vcc
	s_and_b64 s[8:9], s[92:93], exec
	v_lshlrev_b32_e32 v177, 2, v0
	v_xor_b32_e32 v0, 32, v209
	s_cselect_b32 s0, 2, 4
	s_and_b64 s[8:9], s[12:13], exec
	v_cmp_lt_i32_e32 vcc, v0, v3
	v_add_u32_e32 v3, 0x400, v73
	s_cselect_b32 s57, 0, s0
	v_cndmask_b32_e32 v0, v209, v0, vcc
	s_and_b64 s[8:9], s[92:93], exec
	v_ashrrev_i32_e32 v180, 3, v3
	v_add_u32_e32 v3, 0x600, v73
	v_lshlrev_b32_e32 v178, 2, v0
	s_cselect_b32 s0, 12, 10
	s_and_b64 s[8:9], s[12:13], exec
	v_add_u32_e32 v0, 0x200, v73
	v_ashrrev_i32_e32 v181, 3, v3
	v_lshlrev_b32_e32 v3, 1, v73
	s_cselect_b32 s99, 14, s0
	v_ashrrev_i32_e32 v179, 3, v0
	v_and_b32_e32 v182, 0xfe, v3
	v_ashrrev_i32_e32 v3, 4, v73
	v_ashrrev_i32_e32 v0, 4, v0
	s_ashr_i32 s0, s24, 31
	v_and_b32_e32 v124, -8, v3
	v_and_b32_e32 v126, -8, v0
	v_mov_b32_e32 v121, s0
	s_movk_i32 s0, 0x210
	v_lshlrev_b32_e32 v128, 2, v74
	v_mul_lo_u32 v78, v124, s0
	v_mul_lo_u32 v79, v126, s0
	s_add_i32 s29, s28, 2
	s_add_i32 s35, s28, 4
	s_add_i32 s34, s28, 6
	s_add_i32 s0, s28, 8
	v_mov_b32_e32 v71, v1
	v_sub_u32_e32 v0, v72, v128
	s_add_i32 s40, s24, 16
	s_lshl_b32 s41, s29, 4
	s_add_i32 s42, s24, 48
	s_lshl_b32 s43, s35, 4
	s_add_i32 s49, s24, 0x50
	s_lshl_b32 s52, s34, 4
	s_add_i32 s48, s24, 0x70
	s_lshl_b32 s53, s0, 4
	v_or_b32_e32 v120, s24, v72
	v_lshl_add_u64 v[122:123], s[10:11], 0, v[70:71]
	v_add_u32_e32 v70, 0x80, v0
	s_movk_i32 s8, 0x90
	v_or_b32_e32 v81, s40, v72
	v_or_b32_e32 v82, s41, v72
	v_or_b32_e32 v83, s42, v72
	v_or_b32_e32 v84, s43, v72
	v_or_b32_e32 v85, s49, v72
	v_or_b32_e32 v86, s52, v72
	v_or_b32_e32 v87, s48, v72
	v_or_b32_e32 v88, s53, v72
	s_movk_i32 s55, 0x81
	v_lshl_add_u32 v3, v74, 4, 0
	v_cmp_eq_u32_e32 vcc, 0, v74
	v_mul_lo_u32 v74, v129, s8
	v_mul_lo_u32 v75, v179, s8
	v_mul_lo_u32 v76, v180, s8
	v_mul_lo_u32 v77, v181, s8
	v_mul_lo_u32 v80, v120, s8
	v_mul_lo_u32 v81, v81, s8
	v_mul_lo_u32 v82, v82, s8
	v_mul_lo_u32 v83, v83, s8
	v_mul_lo_u32 v84, v84, s8
	v_mul_lo_u32 v85, v85, s8
	v_mul_lo_u32 v86, v86, s8
	v_mul_lo_u32 v87, v87, s8
	v_mul_lo_u32 v88, v88, s8
	v_cmp_gt_u32_e64 s[8:9], s55, v70
	v_lshl_add_u32 v183, v70, 2, s58
	v_add_u32_e32 v70, 0x7f, v0
	v_cmp_gt_u32_e64 s[10:11], s55, v70
	v_lshl_add_u32 v184, v70, 2, s58
	v_add_u32_e32 v70, 0x7e, v0
	v_cmp_gt_u32_e64 s[12:13], s55, v70
	v_lshl_add_u32 v185, v70, 2, s58
	v_add_u32_e32 v70, 0x7d, v0
	v_lshl_add_u32 v187, v0, 2, s58
	v_cmp_lt_i32_e64 s[16:17], -1, v0
	v_cmp_lt_i32_e64 s[18:19], 0, v0
	v_cmp_lt_i32_e64 s[20:21], 1, v0
	v_cmp_lt_i32_e64 s[22:23], 2, v0
	v_or_b32_e32 v0, s24, v128
	s_movk_i32 s54, 0x7f
	s_and_b64 s[38:39], s[88:89], vcc
	v_cmp_gt_u32_e64 s[14:15], s55, v70
	v_lshl_add_u32 v186, v70, 2, s58
	v_cmp_lt_i32_e32 vcc, s54, v0
	v_or_b32_e32 v70, 1, v128
	s_and_b64 s[24:25], s[8:9], vcc
	v_sub_u32_e32 v89, v72, v70
	v_writelane_b32 v254, s24, 39
	v_add_u32_e32 v90, 0x80, v89
	s_movk_i32 s59, 0x7e
	v_lshl_add_u32 v191, v89, 2, s58
	v_or_b32_e32 v89, 2, v128
	v_writelane_b32 v254, s25, 40
	v_cmp_gt_u32_e32 vcc, s55, v90
	v_cmp_lt_i32_e64 s[24:25], s59, v0
	v_sub_u32_e32 v90, v72, v89
	s_and_b64 s[24:25], vcc, s[24:25]
	v_add_u32_e32 v91, 0x80, v90
	v_writelane_b32 v254, s24, 41
	v_cmp_gt_u32_e32 vcc, s55, v91
	v_or_b32_e32 v91, 2, v0
	v_writelane_b32 v254, s25, 42
	v_cmp_lt_i32_e64 s[24:25], s54, v91
	v_lshl_add_u32 v192, v90, 2, s58
	v_or_b32_e32 v90, 3, v128
	s_and_b64 s[24:25], vcc, s[24:25]
	v_sub_u32_e32 v91, v72, v90
	v_writelane_b32 v254, s24, 35
	v_add_u32_e32 v92, 0x80, v91
	v_or_b32_e32 v0, 3, v0
	v_writelane_b32 v254, s25, 36
	v_cmp_gt_u32_e32 vcc, s55, v92
	v_cmp_lt_i32_e64 s[24:25], s54, v0
	s_and_b64 s[24:25], vcc, s[24:25]
	v_or_b32_e32 v0, s40, v128
	v_writelane_b32 v254, s24, 25
	v_lshlrev_b32_e32 v176, 2, v2
	v_lshlrev_b32_e32 v2, 4, v73
	v_writelane_b32 v254, s25, 26
	v_or_b32_e32 v73, -16, v73
	v_cmp_lt_i32_e64 s[24:25], s54, v0
	v_lshl_add_u32 v193, v91, 2, s58
	v_sub_u32_e32 v91, v73, v128
	v_writelane_b32 v254, s24, 33
	v_lshl_add_u32 v194, v91, 2, s58
	v_sub_u32_e32 v91, v73, v70
	v_writelane_b32 v254, s25, 34
	v_cmp_lt_i32_e64 s[24:25], s59, v0
	v_lshl_add_u32 v195, v91, 2, s58
	v_or_b32_e32 v91, 2, v0
	v_writelane_b32 v254, s24, 27
	v_or_b32_e32 v0, 3, v0
	v_or_b32_e32 v93, 0xffffff80, v72
	v_writelane_b32 v254, s25, 28
	v_cmp_lt_i32_e64 s[24:25], s54, v91
	v_sub_u32_e32 v91, v73, v89
	v_lshl_add_u32 v196, v91, 2, s58
	v_writelane_b32 v254, s24, 43
	v_sub_u32_e32 v94, v93, v128
	v_add_u32_e32 v95, 0x80, v94
	v_writelane_b32 v254, s25, 44
	v_cmp_lt_i32_e64 s[24:25], s54, v0
	v_sub_u32_e32 v0, v73, v90
	v_lshl_add_u32 v197, v0, 2, s58
	v_writelane_b32 v254, s24, 37
	v_or_b32_e32 v0, s41, v128
	v_or_b32_e32 v73, 0xffffffe0, v72
	v_writelane_b32 v254, s25, 38
	v_cmp_lt_i32_e64 s[24:25], s54, v0
	v_sub_u32_e32 v91, v73, v128
	v_lshl_add_u32 v198, v91, 2, s58
	v_writelane_b32 v254, s24, 29
	v_sub_u32_e32 v91, v73, v70
	v_lshl_add_u32 v200, v91, 2, s58
	v_writelane_b32 v254, s25, 30
	v_cmp_lt_i32_e64 s[24:25], s59, v0
	v_or_b32_e32 v91, 2, v0
	v_or_b32_e32 v0, 3, v0
	v_writelane_b32 v254, s24, 31
	v_or_b32_e32 v92, s53, v128
	v_cmp_gt_u32_e32 vcc, s55, v95
	v_writelane_b32 v254, s25, 32
	v_cmp_lt_i32_e64 s[24:25], s54, v91
	v_sub_u32_e32 v91, v73, v89
	v_lshl_add_u32 v201, v91, 2, s58
	v_writelane_b32 v254, s24, 45
	v_sub_u32_e32 v95, v93, v70
	v_cmp_lt_i32_e64 s[64:65], s54, v92
	v_writelane_b32 v254, s25, 46
	v_cmp_lt_i32_e64 s[24:25], s54, v0
	v_sub_u32_e32 v0, v73, v90
	v_lshl_add_u32 v202, v0, 2, s58
	v_writelane_b32 v254, s24, 47
	v_or_b32_e32 v0, s42, v128
	v_or_b32_e32 v73, 0xffffffd0, v72
	v_writelane_b32 v254, s25, 48
	v_cmp_lt_i32_e64 s[24:25], s54, v0
	v_sub_u32_e32 v91, v73, v128
	v_lshl_add_u32 v203, v91, 2, s58
	v_writelane_b32 v254, s24, 49
	v_sub_u32_e32 v91, v73, v70
	v_lshl_add_u32 v210, v91, 2, s58
	v_writelane_b32 v254, s25, 50
	v_cmp_lt_i32_e64 s[24:25], s59, v0
	v_or_b32_e32 v91, 2, v0
	v_or_b32_e32 v0, 3, v0
	v_writelane_b32 v254, s24, 51
	v_add_u32_e32 v96, 0x80, v95
	s_and_b64 s[40:41], vcc, s[64:65]
	v_writelane_b32 v254, s25, 52
	v_cmp_lt_i32_e64 s[24:25], s54, v91
	v_sub_u32_e32 v91, v73, v89
	v_lshl_add_u32 v211, v91, 2, s58
	v_writelane_b32 v254, s24, 53
	v_cmp_gt_u32_e32 vcc, s55, v96
	v_sub_u32_e32 v96, v93, v89
	v_writelane_b32 v254, s25, 54
	v_cmp_lt_i32_e64 s[24:25], s54, v0
	v_sub_u32_e32 v0, v73, v90
	v_lshl_add_u32 v212, v0, 2, s58
	v_writelane_b32 v254, s24, 55
	v_or_b32_e32 v0, s43, v128
	v_or_b32_e32 v73, 0xffffffc0, v72
	v_writelane_b32 v254, s25, 56
	v_cmp_lt_i32_e64 s[24:25], s54, v0
	v_sub_u32_e32 v91, v73, v128
	v_lshl_add_u32 v213, v91, 2, s58
	v_writelane_b32 v254, s24, 57
	v_sub_u32_e32 v91, v73, v70
	v_lshl_add_u32 v214, v91, 2, s58
	v_writelane_b32 v254, s25, 58
	v_cmp_lt_i32_e64 s[24:25], s59, v0
	v_or_b32_e32 v91, 2, v0
	v_or_b32_e32 v0, 3, v0
	v_writelane_b32 v254, s24, 59
	v_cmp_lt_i32_e64 s[64:65], s59, v92
	v_add_u32_e32 v97, 0x80, v96
	v_writelane_b32 v254, s25, 60
	v_cmp_lt_i32_e64 s[24:25], s54, v91
	v_sub_u32_e32 v91, v73, v89
	v_lshl_add_u32 v215, v91, 2, s58
	v_writelane_b32 v254, s24, 61
	s_and_b64 s[42:43], vcc, s[64:65]
	v_cmp_gt_u32_e32 vcc, s55, v97
	v_writelane_b32 v254, s25, 62
	v_cmp_lt_i32_e64 s[24:25], s54, v0
	v_sub_u32_e32 v0, v73, v90
	v_or_b32_e32 v73, 0xffffffb0, v72
	v_sub_u32_e32 v91, v73, v128
	v_or_b32_e32 v97, 2, v92
	v_sub_u32_e32 v93, v93, v90
	v_writelane_b32 v254, s24, 63
	v_lshl_add_u32 v216, v0, 2, s58
	v_or_b32_e32 v0, s49, v128
	v_lshl_add_u32 v217, v91, 2, s58
	v_sub_u32_e32 v91, v73, v70
	v_cmp_lt_i32_e64 s[64:65], s54, v97
	v_add_u32_e32 v97, 0x80, v93
	v_or_b32_e32 v92, 3, v92
	v_writelane_b32 v255, s25, 0
	v_cmp_lt_i32_e64 s[24:25], s54, v0
	v_cmp_lt_i32_e64 s[60:61], s59, v0
	v_lshl_add_u32 v218, v91, 2, s58
	v_or_b32_e32 v91, 2, v0
	v_or_b32_e32 v0, 3, v0
	s_and_b64 s[88:89], vcc, s[64:65]
	v_cmp_gt_u32_e32 vcc, s55, v97
	v_cmp_lt_i32_e64 s[64:65], s54, v92
	s_and_b64 s[92:93], vcc, s[64:65]
	v_cmp_lt_i32_e64 s[64:65], s54, v0
	v_sub_u32_e32 v0, v73, v90
	v_cmp_lt_i32_e64 s[62:63], s54, v91
	v_sub_u32_e32 v91, v73, v89
	v_lshl_add_u32 v220, v0, 2, s58
	v_or_b32_e32 v0, 0xffffffa0, v72
	v_lshl_add_u32 v219, v91, 2, s58
	v_or_b32_e32 v91, s52, v128
	v_sub_u32_e32 v99, v0, v70
	v_lshl_add_u32 v222, v99, 2, s58
	v_or_b32_e32 v99, 2, v91
	v_sub_u32_e32 v97, v0, v128
	v_cmp_lt_i32_e64 s[70:71], s54, v99
	v_sub_u32_e32 v99, v0, v89
	v_sub_u32_e32 v0, v0, v90
	v_writelane_b32 v255, s24, 1
	v_lshl_add_u32 v224, v0, 2, s58
	v_or_b32_e32 v0, 0xffffff90, v72
	v_and_b32_e32 v2, 0x70, v2
	v_sub_u32_e32 v71, v3, v68
	v_writelane_b32 v255, s25, 2
	v_or_b32_e32 v73, s48, v128
	v_lshl_add_u32 v223, v99, 2, s58
	v_sub_u32_e32 v99, v0, v128
	v_sub_u32_e32 v70, v0, v70
	v_sub_u32_e32 v89, v0, v89
	v_sub_u32_e32 v0, v0, v90
	v_readlane_b32 s24, v254, 12
	v_add_u32_e32 v2, 0, v2
	v_lshl_add_u32 v92, s28, 5, v71
	v_cmp_lt_i32_e64 s[66:67], s54, v91
	v_lshl_add_u32 v221, v97, 2, s58
	v_lshl_add_u32 v97, s29, 5, v71
	v_lshl_add_u32 v98, s35, 5, v71
	v_cmp_lt_i32_e64 s[68:69], s59, v91
	v_lshl_add_u32 v100, s34, 5, v71
	v_lshl_add_u32 v71, s0, 5, v71
	v_or_b32_e32 v91, 3, v91
	v_lshl_add_u32 v226, v70, 2, s58
	v_or_b32_e32 v70, 2, v73
	v_lshl_add_u32 v227, v89, 2, s58
	v_or_b32_e32 v89, 3, v73
	v_lshl_add_u32 v228, v0, 2, s58
	v_mul_u32_u24_e32 v72, 0x210, v72
	v_lshlrev_b32_e32 v0, 1, v68
	v_readlane_b32 s25, v254, 13
	v_ashrrev_i32_e32 v125, 31, v124
	v_ashrrev_i32_e32 v127, 31, v126
	v_add_u32_e32 v188, -4, v187
	v_add_u32_e32 v189, -8, v187
	v_add_u32_e32 v190, -12, v187
	v_lshl_add_u32 v225, v99, 2, s58
	v_lshl_add_u32 v229, v94, 2, s58
	v_lshl_add_u32 v230, v95, 2, s58
	v_lshl_add_u32 v231, v96, 2, s58
	v_lshl_add_u32 v232, v93, 2, s58
	v_lshl_add_u64 v[132:133], s[24:25], 0, v[0:1]
	v_add_u32_e32 v233, v2, v74
	v_add_u32_e32 v234, v2, v75
	v_add_u32_e32 v235, v2, v76
	v_add_u32_e32 v236, v2, v77
	v_add_u32_e32 v237, v69, v78
	v_add_u32_e32 v238, v69, v79
	v_add_u32_e32 v239, v3, v80
	v_add_u32_e32 v240, v3, v81
	v_add_u32_e32 v241, v3, v82
	v_add_u32_e32 v242, v3, v83
	v_add_u32_e32 v243, v3, v84
	v_add_u32_e32 v244, v3, v85
	v_add_u32_e32 v245, v3, v86
	v_add_u32_e32 v246, v3, v87
	v_add_u32_e32 v247, v3, v88
	v_add_u32_e32 v248, v92, v72
	v_add_u32_e32 v249, v97, v72
	v_add_u32_e32 v250, v98, v72
	v_add_u32_e32 v251, v100, v72
	v_add_u32_e32 v206, v71, v72
	v_readlane_b32 s58, v252, 47
	v_cmp_lt_i32_e64 s[72:73], s54, v91
	v_cmp_lt_i32_e64 s[74:75], s54, v73
	v_cmp_lt_i32_e64 s[76:77], s59, v73
	v_cmp_lt_i32_e64 s[78:79], s54, v70
	v_cmp_lt_i32_e64 s[80:81], s54, v89
	s_branch .LBB0_316
.LBB0_315:
	s_or_b64 exec, exec, s[24:25]
	v_add_u32_e32 v173, s100, v173
	v_add_u32_e32 v183, s100, v183
	v_add_u32_e32 v184, s100, v184
	v_add_u32_e32 v185, s100, v185
	v_add_u32_e32 v186, s100, v186
	v_add_u32_e32 v187, s100, v187
	v_add_u32_e32 v188, s100, v188
	v_add_u32_e32 v189, s100, v189
	v_add_u32_e32 v190, s100, v190
	v_add_u32_e32 v191, s100, v191
	v_add_u32_e32 v192, s100, v192
	v_add_u32_e32 v193, s100, v193
	v_add_u32_e32 v194, s100, v194
	v_add_u32_e32 v195, s100, v195
	v_add_u32_e32 v196, s100, v196
	v_add_u32_e32 v197, s100, v197
	v_add_u32_e32 v198, s100, v198
	v_add_u32_e32 v200, s100, v200
	v_add_u32_e32 v201, s100, v201
	v_add_u32_e32 v202, s100, v202
	v_add_u32_e32 v203, s100, v203
	v_add_u32_e32 v206, s100, v206
	v_add_u32_e32 v210, s100, v210
	v_add_u32_e32 v211, s100, v211
	v_add_u32_e32 v212, s100, v212
	v_add_u32_e32 v213, s100, v213
	v_add_u32_e32 v214, s100, v214
	v_add_u32_e32 v215, s100, v215
	v_add_u32_e32 v216, s100, v216
	v_add_u32_e32 v217, s100, v217
	v_add_u32_e32 v218, s100, v218
	v_add_u32_e32 v219, s100, v219
	v_add_u32_e32 v220, s100, v220
	v_add_u32_e32 v221, s100, v221
	v_add_u32_e32 v222, s100, v222
	v_add_u32_e32 v223, s100, v223
	v_add_u32_e32 v224, s100, v224
	v_add_u32_e32 v225, s100, v225
	v_add_u32_e32 v226, s100, v226
	v_add_u32_e32 v227, s100, v227
	v_add_u32_e32 v228, s100, v228
	v_add_u32_e32 v229, s100, v229
	v_add_u32_e32 v230, s100, v230
	v_add_u32_e32 v231, s100, v231
	v_add_u32_e32 v232, s100, v232
	v_add_u32_e32 v233, s100, v233
	v_add_u32_e32 v234, s100, v234
	v_add_u32_e32 v235, s100, v235
	v_add_u32_e32 v236, s100, v236
	v_add_u32_e32 v239, s100, v239
	v_add_u32_e32 v240, s100, v240
	v_add_u32_e32 v241, s100, v241
	v_add_u32_e32 v242, s100, v242
	v_add_u32_e32 v243, s100, v243
	v_add_u32_e32 v244, s100, v244
	v_add_u32_e32 v245, s100, v245
	v_add_u32_e32 v246, s100, v246
	v_add_u32_e32 v247, s100, v247
	v_add_u32_e32 v237, s100, v237
	v_add_u32_e32 v238, s100, v238
	v_add_u32_e32 v248, s100, v248
	v_add_u32_e32 v249, s100, v249
	v_add_u32_e32 v250, s100, v250
	v_add_u32_e32 v251, s100, v251
	s_sub_i32 s100, 0, s100
	s_and_b64 vcc, exec, s[28:29]
	s_mov_b32 s58, s59
	s_waitcnt vmcnt(8)
	v_mov_b32_e32 v199, v207
	s_waitcnt vmcnt(7)
	v_mov_b32_e32 v130, v138
	v_mov_b32_e32 v131, v139
	s_waitcnt vmcnt(6)
	v_mov_b32_e32 v118, v136
	v_mov_b32_e32 v119, v137
	s_waitcnt vmcnt(5)
	v_mov_b32_e32 v116, v134
	v_mov_b32_e32 v117, v135
	s_waitcnt vmcnt(4)
	v_mov_b32_e32 v114, v2
	v_mov_b32_e32 v115, v3
	s_cbranch_vccnz .LBB0_438
.LBB0_316:
	s_and_saveexec_b64 s[24:25], s[6:7]
	s_cbranch_execz .LBB0_318
	s_waitcnt vmcnt(0)
	v_mul_f32_e32 v0, 0x3fb8aa3b, v172
	ds_write_b32 v173, v0
